# latent attention: the 64 per-element rel-pos-bias loads (each exec-branched + vmcnt(0)) hoisted and issued together after the address regs exist, consumed with counted vmcnt, fmac+cndmask instead of e
# speedup vs baseline: 1.0135x; 1.0135x over previous
.LBB0_388:
	v_mov_b32_e32 v247, 0xf149f2ca
	v_med3_i32 v4, s79, 4, 60
	v_lshlrev_b32_e32 v164, 6, v4
	v_or_b32_e32 v24, v164, v137
	s_add_i32 s16, s73, s79
	v_add_u32_e32 v148, 0xffffff00, v164
	v_ashrrev_i32_e32 v25, 31, v24
	v_readfirstlane_b32 s18, v4
	v_med3_i32 v5, s16, 4, 60
	v_add_u32_e32 v4, v148, v137
	v_add_u32_e32 v8, v55, v164
	v_add_u32_e32 v12, v140, v164
	v_add_u32_e32 v16, v141, v164
	v_lshlrev_b64 v[20:21], 12, v[24:25]
	v_or_b32_e32 v24, 64, v24
	v_add_u32_e32 v28, v142, v164
	v_add_u32_e32 v32, v143, v164
	v_readfirstlane_b32 s19, v5
	v_ashrrev_i32_e32 v5, 31, v4
	v_ashrrev_i32_e32 v9, 31, v8
	v_ashrrev_i32_e32 v13, 31, v12
	v_ashrrev_i32_e32 v17, 31, v16
	v_ashrrev_i32_e32 v25, 31, v24
	v_ashrrev_i32_e32 v29, 31, v28
	v_ashrrev_i32_e32 v33, 31, v32
	v_lshlrev_b64 v[4:5], 12, v[4:5]
	v_lshlrev_b64 v[8:9], 12, v[8:9]
	v_lshlrev_b64 v[12:13], 12, v[12:13]
	v_lshlrev_b64 v[16:17], 12, v[16:17]
	v_lshlrev_b64 v[24:25], 12, v[24:25]
	v_lshlrev_b64 v[28:29], 12, v[28:29]
	v_lshlrev_b64 v[32:33], 12, v[32:33]
	v_lshl_add_u64 v[4:5], v[78:79], 0, v[4:5]
	v_lshl_add_u64 v[8:9], v[78:79], 0, v[8:9]
	v_lshl_add_u64 v[12:13], v[78:79], 0, v[12:13]
	v_lshl_add_u64 v[16:17], v[78:79], 0, v[16:17]
	v_lshl_add_u64 v[20:21], v[78:79], 0, v[20:21]
	v_lshl_add_u64 v[24:25], v[78:79], 0, v[24:25]
	v_lshl_add_u64 v[28:29], v[78:79], 0, v[28:29]
	v_lshl_add_u64 v[32:33], v[78:79], 0, v[32:33]
	s_barrier
	global_load_dwordx4 v[4:7], v[4:5], off offset:2048
	s_cmp_lt_u32 s79, 60
	global_load_dwordx4 v[8:11], v[8:9], off offset:2048
	s_cselect_b64 s[16:17], -1, 0
	global_load_dwordx4 v[12:15], v[12:13], off offset:2048
	s_cmp_gt_u32 s79, 59
	global_load_dwordx4 v[16:19], v[16:17], off offset:2048
	s_nop 0
	global_load_dwordx4 v[20:23], v[20:21], off offset:2048
	s_nop 0
	global_load_dwordx4 v[24:27], v[24:25], off offset:2048
	s_nop 0
	global_load_dwordx4 v[28:31], v[28:29], off offset:2048
	s_nop 0
	global_load_dwordx4 v[32:35], v[32:33], off offset:2048
	s_cbranch_scc1 .LBB0_390
	v_add_u32_e32 v0, v144, v164
	v_ashrrev_i32_e32 v1, 31, v0
	v_lshlrev_b64 v[0:1], 12, v[0:1]
	v_lshl_add_u64 v[0:1], v[78:79], 0, v[0:1]
	global_load_dwordx4 v[0:3], v[0:1], off offset:2048

.LBB0_392:
	v_add_u32_e32 v16, s6, v147
	v_med3_i32 v4, s80, 4, 60
	v_ashrrev_i32_e32 v17, 31, v16
	v_add_u32_e32 v22, s81, v4
	v_lshlrev_b64 v[4:5], 12, v[16:17]
	v_lshl_add_u64 v[4:5], v[56:57], 0, v[4:5]
	global_load_dwordx4 v[8:11], v[4:5], off
	s_nop 0
	global_load_dwordx4 v[4:7], v[4:5], off offset:64
	s_sub_i32 s18, s19, s18
	v_lshl_add_u32 v18, s18, 13, v146
	v_add_u32_e32 v26, v18, v138
	s_waitcnt lgkmcnt(0)
	s_barrier
	ds_read_b128 v[12:15], v26
	v_add_u32_e32 v27, v18, v139
	ds_read_b128 v[18:21], v27
	s_waitcnt vmcnt(1) lgkmcnt(1)
	v_mfma_f32_16x16x32_bf16 v[12:15], v[12:15], v[8:11], 0
	s_waitcnt vmcnt(0) lgkmcnt(0)
	v_mfma_f32_16x16x32_bf16 v[12:15], v[18:21], v[4:7], v[12:15]
	v_mul_lo_u32 v18, v22, 31
	v_ashrrev_i32_e32 v19, 31, v18
	v_lshlrev_b64 v[18:19], 2, v[18:19]
	v_lshl_add_u64 v[32:33], s[4:5], 0, v[18:19]
	v_lshl_add_u64 v[18:19], v[62:63], 2, v[32:33]
	v_lshl_add_u64 v[20:21], v[64:65], 2, v[32:33]
	v_lshl_add_u64 v[22:23], v[66:67], 2, v[32:33]
	v_lshl_add_u64 v[24:25], v[68:69], 2, v[32:33]
	global_load_dword v166, v[18:19], off offset:432
	global_load_dword v165, v[20:21], off offset:432
	global_load_dword v168, v[22:23], off offset:432
	global_load_dword v167, v[24:25], off offset:432
	global_load_dword v175, v[18:19], off offset:556
	global_load_dword v173, v[20:21], off offset:556
	global_load_dword v176, v[22:23], off offset:556
	global_load_dword v174, v[24:25], off offset:556
	global_load_dword v183, v[18:19], off offset:680
	global_load_dword v181, v[20:21], off offset:680
	global_load_dword v184, v[22:23], off offset:680
	global_load_dword v182, v[24:25], off offset:680
	global_load_dword v192, v[18:19], off offset:804
	global_load_dword v190, v[20:21], off offset:804
	global_load_dword v193, v[22:23], off offset:804
	global_load_dword v191, v[24:25], off offset:804
	global_load_dword v200, v[18:19], off offset:928
	global_load_dword v198, v[20:21], off offset:928
	global_load_dword v201, v[22:23], off offset:928
	global_load_dword v199, v[24:25], off offset:928
	global_load_dword v208, v[18:19], off offset:1052
	global_load_dword v206, v[20:21], off offset:1052
	global_load_dword v209, v[22:23], off offset:1052
	global_load_dword v207, v[24:25], off offset:1052
	global_load_dword v216, v[18:19], off offset:1176
	global_load_dword v214, v[20:21], off offset:1176
	global_load_dword v217, v[22:23], off offset:1176
	global_load_dword v215, v[24:25], off offset:1176
	global_load_dword v224, v[18:19], off offset:1300
	global_load_dword v222, v[20:21], off offset:1300
	global_load_dword v225, v[22:23], off offset:1300
	global_load_dword v223, v[24:25], off offset:1300
	s_waitcnt vmcnt(28)
	v_fmac_f32_e32 v166, 0x3e000000, v12
	v_cndmask_b32_e64 v166, v247, v166, s[28:29]
	v_fmac_f32_e32 v165, 0x3e000000, v13
	v_cndmask_b32_e64 v165, v247, v165, s[48:49]
	v_fmac_f32_e32 v168, 0x3e000000, v14
	v_cndmask_b32_e64 v168, v247, v168, s[24:25]
	v_fmac_f32_e32 v167, 0x3e000000, v15
	v_cndmask_b32_e64 v167, v247, v167, s[96:97]
	ds_read_b128 v[12:15], v26 offset:512
	ds_read_b128 v[26:29], v27 offset:512
	s_waitcnt lgkmcnt(1)
	v_mfma_f32_16x16x32_bf16 v[12:15], v[12:15], v[8:11], 0
	s_waitcnt lgkmcnt(0)
	v_mfma_f32_16x16x32_bf16 v[12:15], v[26:29], v[4:7], v[12:15]
	v_lshl_add_u64 v[26:27], v[70:71], 2, v[32:33]
	v_lshl_add_u64 v[28:29], v[72:73], 2, v[32:33]
	v_lshl_add_u64 v[30:31], v[74:75], 2, v[32:33]
	v_lshl_add_u64 v[32:33], v[76:77], 2, v[32:33]
	global_load_dword v171, v[26:27], off offset:432
	global_load_dword v169, v[28:29], off offset:432
	global_load_dword v172, v[30:31], off offset:432
	global_load_dword v170, v[32:33], off offset:432
	global_load_dword v179, v[26:27], off offset:556
	global_load_dword v177, v[28:29], off offset:556
	global_load_dword v180, v[30:31], off offset:556
	global_load_dword v178, v[32:33], off offset:556
	global_load_dword v187, v[26:27], off offset:680
	global_load_dword v185, v[28:29], off offset:680
	global_load_dword v189, v[30:31], off offset:680
	global_load_dword v186, v[32:33], off offset:680
	global_load_dword v196, v[26:27], off offset:804
	global_load_dword v194, v[28:29], off offset:804
	global_load_dword v197, v[30:31], off offset:804
	global_load_dword v195, v[32:33], off offset:804
	global_load_dword v204, v[26:27], off offset:928
	global_load_dword v202, v[28:29], off offset:928
	global_load_dword v205, v[30:31], off offset:928
	global_load_dword v203, v[32:33], off offset:928
	global_load_dword v212, v[26:27], off offset:1052
	global_load_dword v210, v[28:29], off offset:1052
	global_load_dword v213, v[30:31], off offset:1052
	global_load_dword v211, v[32:33], off offset:1052
	global_load_dword v220, v[26:27], off offset:1176
	global_load_dword v218, v[28:29], off offset:1176
	global_load_dword v221, v[30:31], off offset:1176
	global_load_dword v219, v[32:33], off offset:1176
	global_load_dword v228, v[26:27], off offset:1300
	global_load_dword v226, v[28:29], off offset:1300
	global_load_dword v229, v[30:31], off offset:1300
	global_load_dword v227, v[32:33], off offset:1300
	s_waitcnt vmcnt(28)
	v_fmac_f32_e32 v171, 0x3e000000, v12
	v_cndmask_b32_e64 v171, v247, v171, s[26:27]
	v_fmac_f32_e32 v169, 0x3e000000, v13
	v_cndmask_b32_e64 v169, v247, v169, s[2:3]
	v_fmac_f32_e32 v172, 0x3e000000, v14
	v_cndmask_b32_e64 v172, v247, v172, s[64:65]
	v_fmac_f32_e32 v170, 0x3e000000, v15
	v_cndmask_b32_e64 v170, v247, v170, s[0:1]
	s_add_i32 s19, s18, 1
	v_lshl_add_u32 v35, s19, 13, v146
	v_add_u32_e32 v34, v35, v138
	ds_read_b128 v[12:15], v34
	v_add_u32_e32 v35, v35, v139
	ds_read_b128 v[80:83], v35
	s_waitcnt lgkmcnt(1)
	v_mfma_f32_16x16x32_bf16 v[12:15], v[12:15], v[8:11], 0
	s_waitcnt lgkmcnt(0)
	v_mfma_f32_16x16x32_bf16 v[12:15], v[80:83], v[4:7], v[12:15]
	s_waitcnt vmcnt(56)
	s_nop 6
	v_fmac_f32_e32 v175, 0x3e000000, v12
	v_cndmask_b32_e64 v175, v247, v175, s[28:29]
	v_fmac_f32_e32 v173, 0x3e000000, v13
	v_cndmask_b32_e64 v173, v247, v173, s[48:49]
	v_fmac_f32_e32 v176, 0x3e000000, v14
	v_cndmask_b32_e64 v176, v247, v176, s[24:25]
	v_fmac_f32_e32 v174, 0x3e000000, v15
	v_cndmask_b32_e64 v174, v247, v174, s[96:97]
	ds_read_b128 v[12:15], v34 offset:512
	ds_read_b128 v[80:83], v35 offset:512
	s_waitcnt lgkmcnt(1)
	v_mfma_f32_16x16x32_bf16 v[12:15], v[12:15], v[8:11], 0
	s_waitcnt lgkmcnt(0)
	v_mfma_f32_16x16x32_bf16 v[12:15], v[80:83], v[4:7], v[12:15]
	s_waitcnt vmcnt(24)
	s_nop 6
	v_fmac_f32_e32 v179, 0x3e000000, v12
	v_cndmask_b32_e64 v179, v247, v179, s[26:27]
	v_fmac_f32_e32 v177, 0x3e000000, v13
	v_cndmask_b32_e64 v177, v247, v177, s[2:3]
	v_fmac_f32_e32 v180, 0x3e000000, v14
	v_cndmask_b32_e64 v180, v247, v180, s[64:65]
	v_fmac_f32_e32 v178, 0x3e000000, v15
	v_cndmask_b32_e64 v178, v247, v178, s[0:1]
	s_add_i32 s20, s18, 2
	v_lshl_add_u32 v35, s20, 13, v146
	v_add_u32_e32 v34, v35, v138
	ds_read_b128 v[12:15], v34
	v_add_u32_e32 v35, v35, v139
	ds_read_b128 v[80:83], v35
	s_waitcnt lgkmcnt(1)
	v_mfma_f32_16x16x32_bf16 v[12:15], v[12:15], v[8:11], 0
	s_waitcnt lgkmcnt(0)
	v_mfma_f32_16x16x32_bf16 v[12:15], v[80:83], v[4:7], v[12:15]
	s_waitcnt vmcnt(52)
	s_nop 6
	v_fmac_f32_e32 v183, 0x3e000000, v12
	v_cndmask_b32_e64 v183, v247, v183, s[28:29]
	v_fmac_f32_e32 v181, 0x3e000000, v13
	v_cndmask_b32_e64 v181, v247, v181, s[48:49]
	v_fmac_f32_e32 v184, 0x3e000000, v14
	v_cndmask_b32_e64 v184, v247, v184, s[24:25]
	v_fmac_f32_e32 v182, 0x3e000000, v15
	v_cndmask_b32_e64 v182, v247, v182, s[96:97]
	ds_read_b128 v[12:15], v34 offset:512
	ds_read_b128 v[80:83], v35 offset:512
	s_waitcnt lgkmcnt(1)
	v_mfma_f32_16x16x32_bf16 v[12:15], v[12:15], v[8:11], 0
	s_waitcnt lgkmcnt(0)
	v_mfma_f32_16x16x32_bf16 v[12:15], v[80:83], v[4:7], v[12:15]
	s_waitcnt vmcnt(20)
	s_nop 6
	v_fmac_f32_e32 v187, 0x3e000000, v12
	v_cndmask_b32_e64 v187, v247, v187, s[26:27]
	v_fmac_f32_e32 v185, 0x3e000000, v13
	v_cndmask_b32_e64 v185, v247, v185, s[2:3]
	v_fmac_f32_e32 v189, 0x3e000000, v14
	v_cndmask_b32_e64 v189, v247, v189, s[64:65]
	v_fmac_f32_e32 v186, 0x3e000000, v15
	v_cndmask_b32_e64 v186, v247, v186, s[0:1]
	s_add_i32 s21, s18, 3
	v_lshl_add_u32 v35, s21, 13, v146
	v_add_u32_e32 v34, v35, v138
	ds_read_b128 v[12:15], v34
	v_add_u32_e32 v35, v35, v139
	ds_read_b128 v[80:83], v35
	s_waitcnt lgkmcnt(1)
	v_mfma_f32_16x16x32_bf16 v[12:15], v[12:15], v[8:11], 0
	s_waitcnt lgkmcnt(0)
	v_mfma_f32_16x16x32_bf16 v[12:15], v[80:83], v[4:7], v[12:15]
	s_waitcnt vmcnt(48)
	s_nop 6
	v_fmac_f32_e32 v192, 0x3e000000, v12
	v_cndmask_b32_e64 v192, v247, v192, s[28:29]
	v_fmac_f32_e32 v190, 0x3e000000, v13
	v_cndmask_b32_e64 v190, v247, v190, s[48:49]
	v_fmac_f32_e32 v193, 0x3e000000, v14
	v_cndmask_b32_e64 v193, v247, v193, s[24:25]
	v_fmac_f32_e32 v191, 0x3e000000, v15
	v_cndmask_b32_e64 v191, v247, v191, s[96:97]
	ds_read_b128 v[12:15], v34 offset:512
	ds_read_b128 v[80:83], v35 offset:512
	s_waitcnt lgkmcnt(1)
	v_mfma_f32_16x16x32_bf16 v[12:15], v[12:15], v[8:11], 0
	s_waitcnt lgkmcnt(0)
	v_mfma_f32_16x16x32_bf16 v[12:15], v[80:83], v[4:7], v[12:15]
	s_waitcnt vmcnt(16)
	s_nop 6
	v_fmac_f32_e32 v196, 0x3e000000, v12
	v_cndmask_b32_e64 v196, v247, v196, s[26:27]
	v_fmac_f32_e32 v194, 0x3e000000, v13
	v_cndmask_b32_e64 v194, v247, v194, s[2:3]
	v_fmac_f32_e32 v197, 0x3e000000, v14
	v_cndmask_b32_e64 v197, v247, v197, s[64:65]
	v_fmac_f32_e32 v195, 0x3e000000, v15
	v_cndmask_b32_e64 v195, v247, v195, s[0:1]
	s_add_i32 s30, s18, 4
	v_lshl_add_u32 v35, s30, 13, v146
	v_add_u32_e32 v34, v35, v138
	ds_read_b128 v[12:15], v34
	v_add_u32_e32 v35, v35, v139
	ds_read_b128 v[80:83], v35
	s_waitcnt lgkmcnt(1)
	v_mfma_f32_16x16x32_bf16 v[12:15], v[12:15], v[8:11], 0
	s_waitcnt lgkmcnt(0)
	v_mfma_f32_16x16x32_bf16 v[12:15], v[80:83], v[4:7], v[12:15]
	s_waitcnt vmcnt(44)
	s_nop 6
	v_fmac_f32_e32 v200, 0x3e000000, v12
	v_cndmask_b32_e64 v200, v247, v200, s[28:29]
	v_fmac_f32_e32 v198, 0x3e000000, v13
	v_cndmask_b32_e64 v198, v247, v198, s[48:49]
	v_fmac_f32_e32 v201, 0x3e000000, v14
	v_cndmask_b32_e64 v201, v247, v201, s[24:25]
	v_fmac_f32_e32 v199, 0x3e000000, v15
	v_cndmask_b32_e64 v199, v247, v199, s[96:97]
	ds_read_b128 v[12:15], v34 offset:512
	ds_read_b128 v[80:83], v35 offset:512
	s_waitcnt lgkmcnt(1)
	v_mfma_f32_16x16x32_bf16 v[12:15], v[12:15], v[8:11], 0
	s_waitcnt lgkmcnt(0)
	v_mfma_f32_16x16x32_bf16 v[12:15], v[80:83], v[4:7], v[12:15]
	s_waitcnt vmcnt(12)
	s_nop 6
	v_fmac_f32_e32 v204, 0x3e000000, v12
	v_cndmask_b32_e64 v204, v247, v204, s[26:27]
	v_fmac_f32_e32 v202, 0x3e000000, v13
	v_cndmask_b32_e64 v202, v247, v202, s[2:3]
	v_fmac_f32_e32 v205, 0x3e000000, v14
	v_cndmask_b32_e64 v205, v247, v205, s[64:65]
	v_fmac_f32_e32 v203, 0x3e000000, v15
	v_cndmask_b32_e64 v203, v247, v203, s[0:1]
	s_add_i32 s31, s18, 5
	v_lshl_add_u32 v35, s31, 13, v146
	v_add_u32_e32 v34, v35, v138
	ds_read_b128 v[12:15], v34
	v_add_u32_e32 v35, v35, v139
	ds_read_b128 v[80:83], v35
	s_waitcnt lgkmcnt(1)
	v_mfma_f32_16x16x32_bf16 v[12:15], v[12:15], v[8:11], 0
	s_waitcnt lgkmcnt(0)
	v_mfma_f32_16x16x32_bf16 v[12:15], v[80:83], v[4:7], v[12:15]
	s_waitcnt vmcnt(40)
	s_nop 6
	v_fmac_f32_e32 v208, 0x3e000000, v12
	v_cndmask_b32_e64 v208, v247, v208, s[28:29]
	v_fmac_f32_e32 v206, 0x3e000000, v13
	v_cndmask_b32_e64 v206, v247, v206, s[48:49]
	v_fmac_f32_e32 v209, 0x3e000000, v14
	v_cndmask_b32_e64 v209, v247, v209, s[24:25]
	v_fmac_f32_e32 v207, 0x3e000000, v15
	v_cndmask_b32_e64 v207, v247, v207, s[96:97]
	ds_read_b128 v[12:15], v34 offset:512
	ds_read_b128 v[80:83], v35 offset:512
	s_waitcnt lgkmcnt(1)
	v_mfma_f32_16x16x32_bf16 v[12:15], v[12:15], v[8:11], 0
	s_waitcnt lgkmcnt(0)
	v_mfma_f32_16x16x32_bf16 v[12:15], v[80:83], v[4:7], v[12:15]
	s_waitcnt vmcnt(8)
	s_nop 6
	v_fmac_f32_e32 v212, 0x3e000000, v12
	v_cndmask_b32_e64 v212, v247, v212, s[26:27]
	v_fmac_f32_e32 v210, 0x3e000000, v13
	v_cndmask_b32_e64 v210, v247, v210, s[2:3]
	v_fmac_f32_e32 v213, 0x3e000000, v14
	v_cndmask_b32_e64 v213, v247, v213, s[64:65]
	v_fmac_f32_e32 v211, 0x3e000000, v15
	v_cndmask_b32_e64 v211, v247, v211, s[0:1]
	s_add_i32 s33, s18, 6
	v_lshl_add_u32 v35, s33, 13, v146
	v_add_u32_e32 v34, v35, v138
	ds_read_b128 v[12:15], v34
	v_add_u32_e32 v35, v35, v139
	ds_read_b128 v[80:83], v35
	s_waitcnt lgkmcnt(1)
	v_mfma_f32_16x16x32_bf16 v[12:15], v[12:15], v[8:11], 0
	s_waitcnt lgkmcnt(0)
	v_mfma_f32_16x16x32_bf16 v[12:15], v[80:83], v[4:7], v[12:15]
	s_waitcnt vmcnt(36)
	s_nop 6
	v_fmac_f32_e32 v216, 0x3e000000, v12
	v_cndmask_b32_e64 v216, v247, v216, s[28:29]
	v_fmac_f32_e32 v214, 0x3e000000, v13
	v_cndmask_b32_e64 v214, v247, v214, s[48:49]
	v_fmac_f32_e32 v217, 0x3e000000, v14
	v_cndmask_b32_e64 v217, v247, v217, s[24:25]
	v_fmac_f32_e32 v215, 0x3e000000, v15
	v_cndmask_b32_e64 v215, v247, v215, s[96:97]
	ds_read_b128 v[12:15], v34 offset:512
	ds_read_b128 v[80:83], v35 offset:512
	s_waitcnt lgkmcnt(1)
	v_mfma_f32_16x16x32_bf16 v[12:15], v[12:15], v[8:11], 0
	s_waitcnt lgkmcnt(0)
	v_mfma_f32_16x16x32_bf16 v[12:15], v[80:83], v[4:7], v[12:15]
	s_waitcnt vmcnt(4)
	s_nop 6
	v_fmac_f32_e32 v220, 0x3e000000, v12
	v_cndmask_b32_e64 v220, v247, v220, s[26:27]
	v_fmac_f32_e32 v218, 0x3e000000, v13
	v_cndmask_b32_e64 v218, v247, v218, s[2:3]
	v_fmac_f32_e32 v221, 0x3e000000, v14
	v_cndmask_b32_e64 v221, v247, v221, s[64:65]
	v_fmac_f32_e32 v219, 0x3e000000, v15
	v_cndmask_b32_e64 v219, v247, v219, s[0:1]
	s_add_i32 s34, s18, 7
	v_lshl_add_u32 v35, s34, 13, v146
	v_add_u32_e32 v34, v35, v138
	ds_read_b128 v[12:15], v34
	v_add_u32_e32 v35, v35, v139
	ds_read_b128 v[80:83], v35
	s_waitcnt lgkmcnt(1)
	v_mfma_f32_16x16x32_bf16 v[12:15], v[12:15], v[8:11], 0
	s_waitcnt lgkmcnt(0)
	v_mfma_f32_16x16x32_bf16 v[12:15], v[80:83], v[4:7], v[12:15]
	s_waitcnt vmcnt(32)
	s_nop 6
	v_fmac_f32_e32 v224, 0x3e000000, v12
	v_cndmask_b32_e64 v224, v247, v224, s[28:29]
	v_fmac_f32_e32 v222, 0x3e000000, v13
	v_cndmask_b32_e64 v222, v247, v222, s[48:49]
	v_fmac_f32_e32 v225, 0x3e000000, v14
	v_cndmask_b32_e64 v225, v247, v225, s[24:25]
	v_fmac_f32_e32 v223, 0x3e000000, v15
	v_cndmask_b32_e64 v223, v247, v223, s[96:97]
	ds_read_b128 v[12:15], v34 offset:512
	ds_read_b128 v[18:21], v35 offset:512
	s_waitcnt lgkmcnt(1)
	v_mfma_f32_16x16x32_bf16 v[12:15], v[12:15], v[8:11], 0
	s_waitcnt lgkmcnt(0)
	v_mfma_f32_16x16x32_bf16 v[12:15], v[18:21], v[4:7], v[12:15]
	s_waitcnt vmcnt(0)
	s_nop 6
	v_fmac_f32_e32 v228, 0x3e000000, v12
	v_cndmask_b32_e64 v228, v247, v228, s[26:27]
	v_fmac_f32_e32 v226, 0x3e000000, v13
	v_cndmask_b32_e64 v226, v247, v226, s[2:3]
	v_fmac_f32_e32 v229, 0x3e000000, v14
	v_cndmask_b32_e64 v229, v247, v229, s[64:65]
	v_fmac_f32_e32 v227, 0x3e000000, v15
	v_cndmask_b32_e64 v227, v247, v227, s[0:1]
	v_max_f32_e32 v12, v167, v167
	v_max_f32_e32 v13, v168, v168
	v_max_f32_e32 v12, v13, v12
	v_max_f32_e32 v13, v170, v170
	v_max_f32_e32 v14, v172, v172
	v_max_f32_e32 v13, v14, v13
	v_max3_f32 v12, v166, v165, v12
	v_max3_f32 v13, v171, v169, v13
	v_max3_f32 v12, v12, s69, v13
	v_max_f32_e32 v13, v174, v174
	v_max_f32_e32 v14, v176, v176
	v_max_f32_e32 v13, v14, v13
	v_max_f32_e32 v14, v178, v178
	v_max_f32_e32 v15, v180, v180
	v_max_f32_e32 v14, v15, v14
	v_max3_f32 v13, v175, v173, v13
	v_max3_f32 v14, v179, v177, v14
	v_max3_f32 v12, v12, v13, v14
	v_max_f32_e32 v13, v182, v182
	v_max_f32_e32 v14, v184, v184
	v_max_f32_e32 v13, v14, v13
	v_max_f32_e32 v14, v186, v186
	v_max_f32_e32 v15, v189, v189
	v_max_f32_e32 v14, v15, v14
	v_max3_f32 v13, v183, v181, v13
	v_max3_f32 v14, v187, v185, v14
	v_max3_f32 v12, v12, v13, v14
	v_max_f32_e32 v13, v191, v191
	v_max_f32_e32 v14, v193, v193
	v_max_f32_e32 v13, v14, v13
	v_max_f32_e32 v14, v195, v195
	v_max_f32_e32 v15, v197, v197
	v_max_f32_e32 v14, v15, v14
	v_max3_f32 v13, v192, v190, v13
	v_max3_f32 v14, v196, v194, v14
	v_max3_f32 v12, v12, v13, v14
	v_max_f32_e32 v13, v199, v199
	v_max_f32_e32 v14, v201, v201
	v_max_f32_e32 v13, v14, v13
	v_max_f32_e32 v14, v203, v203
	v_max_f32_e32 v15, v205, v205
	v_max_f32_e32 v14, v15, v14
	v_max3_f32 v13, v200, v198, v13
	v_max3_f32 v14, v204, v202, v14
	v_max3_f32 v12, v12, v13, v14
	v_max_f32_e32 v13, v207, v207
	v_max_f32_e32 v14, v209, v209
	v_max_f32_e32 v13, v14, v13
	v_max_f32_e32 v14, v211, v211
	v_max_f32_e32 v15, v213, v213
	v_max_f32_e32 v14, v15, v14
	v_max3_f32 v13, v208, v206, v13
	v_max3_f32 v14, v212, v210, v14
	v_max3_f32 v12, v12, v13, v14
	v_max_f32_e32 v13, v215, v215
	v_max_f32_e32 v14, v217, v217
	v_max_f32_e32 v13, v14, v13
	v_max_f32_e32 v14, v219, v219
	v_max_f32_e32 v15, v221, v221
	v_max_f32_e32 v14, v15, v14
	v_max3_f32 v13, v216, v214, v13
	v_max3_f32 v14, v220, v218, v14
	v_max3_f32 v12, v12, v13, v14
	v_max_f32_e32 v13, v223, v223
	v_max_f32_e32 v14, v225, v225
	v_max_f32_e32 v13, v14, v13
	v_max_f32_e32 v14, v227, v227
	v_max_f32_e32 v15, v229, v229
	v_max_f32_e32 v14, v15, v14
	v_max3_f32 v13, v224, v222, v13
	v_max3_f32 v14, v228, v226, v14
	v_max3_f32 v28, v12, v13, v14
	ds_read_b128 v[12:15], v134
	ds_read_b128 v[18:21], v134 offset:64
	s_waitcnt lgkmcnt(1)
	v_mfma_f32_16x16x32_bf16 v[12:15], v[12:15], v[8:11], 0
	s_and_b64 vcc, exec, s[40:41]
	s_waitcnt lgkmcnt(0)
	v_mfma_f32_16x16x32_bf16 v[18:21], v[18:21], v[4:7], v[12:15]
	s_nop 7
	v_pk_mul_f32 v[12:13], v[20:21], s[12:13] op_sel_hi:[1,0]
	ds_read_b128 v[20:23], v134 offset:576
	ds_read_b128 v[24:27], v134 offset:640
	s_waitcnt lgkmcnt(1)
	v_mfma_f32_16x16x32_bf16 v[20:23], v[20:23], v[8:11], 0
	v_mul_f32_e64 v18, v18, s12
	v_mul_f32_e64 v19, v19, s12
	v_max_f32_e32 v14, v12, v13
	v_max3_f32 v29, v18, v19, v14
	s_waitcnt lgkmcnt(0)
	v_mfma_f32_16x16x32_bf16 v[20:23], v[24:27], v[4:7], v[20:23]
	s_nop 7
	v_pk_mul_f32 v[14:15], v[22:23], s[12:13] op_sel_hi:[1,0]
	v_pk_mul_f32 v[22:23], v[20:21], s[12:13] op_sel_hi:[1,0]
	v_max_f32_e32 v20, v14, v15
	v_max3_f32 v20, v22, v23, v20
	v_max3_f32 v80, v28, v29, v20
	ds_read_b128 v[24:27], v134 offset:4608
	ds_read_b128 v[28:31], v134 offset:4672
	s_waitcnt lgkmcnt(1)
	v_mfma_f32_16x16x32_bf16 v[24:27], v[24:27], v[8:11], 0
	s_waitcnt lgkmcnt(0)
	v_mfma_f32_16x16x32_bf16 v[24:27], v[28:31], v[4:7], v[24:27]
	ds_read_b128 v[28:31], v134 offset:5184
	ds_read_b128 v[32:35], v134 offset:5248
	s_waitcnt lgkmcnt(1)
	v_mfma_f32_16x16x32_bf16 v[28:31], v[28:31], v[8:11], 0
	s_nop 3
	v_mul_f32_e64 v20, v26, s12
	v_mul_f32_e64 v21, v27, s12
	v_pk_mul_f32 v[26:27], v[24:25], s[12:13] op_sel_hi:[1,0]
	v_max_f32_e32 v24, v20, v21
	s_waitcnt lgkmcnt(0)
	v_mfma_f32_16x16x32_bf16 v[28:31], v[32:35], v[4:7], v[28:31]
	v_max3_f32 v81, v26, v27, v24
	s_nop 6
	v_pk_mul_f32 v[24:25], v[30:31], s[12:13] op_sel_hi:[1,0]
	v_pk_mul_f32 v[30:31], v[28:29], s[12:13] op_sel_hi:[1,0]
	v_max_f32_e32 v28, v24, v25
	v_max3_f32 v28, v30, v31, v28
	v_max3_f32 v88, v80, v81, v28
	ds_read_b128 v[32:35], v134 offset:9216
	ds_read_b128 v[80:83], v134 offset:9280
	s_waitcnt lgkmcnt(1)
	v_mfma_f32_16x16x32_bf16 v[32:35], v[32:35], v[8:11], 0
	s_waitcnt lgkmcnt(0)
	v_mfma_f32_16x16x32_bf16 v[32:35], v[80:83], v[4:7], v[32:35]
	ds_read_b128 v[80:83], v134 offset:9792
	ds_read_b128 v[84:87], v134 offset:9856
	s_waitcnt lgkmcnt(1)
	v_mfma_f32_16x16x32_bf16 v[80:83], v[80:83], v[8:11], 0
	s_nop 3
	v_mul_f32_e64 v28, v34, s12
	v_mul_f32_e64 v29, v35, s12
	v_pk_mul_f32 v[34:35], v[32:33], s[12:13] op_sel_hi:[1,0]
	v_max_f32_e32 v32, v28, v29
	s_waitcnt lgkmcnt(0)
	v_mfma_f32_16x16x32_bf16 v[80:83], v[84:87], v[4:7], v[80:83]
	v_max3_f32 v89, v34, v35, v32
	s_nop 6
	v_pk_mul_f32 v[32:33], v[82:83], s[12:13] op_sel_hi:[1,0]
	v_pk_mul_f32 v[82:83], v[80:81], s[12:13] op_sel_hi:[1,0]
	v_max_f32_e32 v80, v32, v33
	v_max3_f32 v80, v82, v83, v80
	v_max3_f32 v96, v88, v89, v80
	ds_read_b128 v[84:87], v134 offset:13824
	ds_read_b128 v[88:91], v134 offset:13888
	s_waitcnt lgkmcnt(1)
	v_mfma_f32_16x16x32_bf16 v[84:87], v[84:87], v[8:11], 0
	s_waitcnt lgkmcnt(0)
	v_mfma_f32_16x16x32_bf16 v[84:87], v[88:91], v[4:7], v[84:87]
	ds_read_b128 v[88:91], v134 offset:14400
	ds_read_b128 v[92:95], v134 offset:14464
	s_waitcnt lgkmcnt(1)
	v_mfma_f32_16x16x32_bf16 v[88:91], v[88:91], v[8:11], 0
	s_nop 3
	v_mul_f32_e64 v80, v86, s12
	v_mul_f32_e64 v81, v87, s12
	v_pk_mul_f32 v[86:87], v[84:85], s[12:13] op_sel_hi:[1,0]
	v_max_f32_e32 v84, v80, v81
	s_waitcnt lgkmcnt(0)
	v_mfma_f32_16x16x32_bf16 v[88:91], v[92:95], v[4:7], v[88:91]
	v_max3_f32 v97, v86, v87, v84
	s_nop 6
	v_pk_mul_f32 v[84:85], v[90:91], s[12:13] op_sel_hi:[1,0]
	v_pk_mul_f32 v[90:91], v[88:89], s[12:13] op_sel_hi:[1,0]
	v_max_f32_e32 v88, v84, v85
	v_max3_f32 v88, v90, v91, v88
	v_max3_f32 v104, v96, v97, v88
	ds_read_b128 v[92:95], v134 offset:18432
	ds_read_b128 v[96:99], v134 offset:18496
	s_waitcnt lgkmcnt(1)
	v_mfma_f32_16x16x32_bf16 v[92:95], v[92:95], v[8:11], 0
	s_waitcnt lgkmcnt(0)
	v_mfma_f32_16x16x32_bf16 v[92:95], v[96:99], v[4:7], v[92:95]
	ds_read_b128 v[96:99], v134 offset:19008
	ds_read_b128 v[100:103], v134 offset:19072
	s_waitcnt lgkmcnt(1)
	v_mfma_f32_16x16x32_bf16 v[96:99], v[96:99], v[8:11], 0
	s_nop 3
	v_mul_f32_e64 v88, v94, s12
	v_mul_f32_e64 v89, v95, s12
	v_pk_mul_f32 v[94:95], v[92:93], s[12:13] op_sel_hi:[1,0]
	v_max_f32_e32 v92, v88, v89
	s_waitcnt lgkmcnt(0)
	v_mfma_f32_16x16x32_bf16 v[96:99], v[100:103], v[4:7], v[96:99]
	v_max3_f32 v105, v94, v95, v92
	s_nop 6
	v_pk_mul_f32 v[92:93], v[98:99], s[12:13] op_sel_hi:[1,0]
	v_pk_mul_f32 v[98:99], v[96:97], s[12:13] op_sel_hi:[1,0]
	v_max_f32_e32 v96, v92, v93
	v_max3_f32 v96, v98, v99, v96
	v_max3_f32 v112, v104, v105, v96
	ds_read_b128 v[100:103], v134 offset:23040
	ds_read_b128 v[104:107], v134 offset:23104
	s_waitcnt lgkmcnt(1)
	v_mfma_f32_16x16x32_bf16 v[100:103], v[100:103], v[8:11], 0
	s_waitcnt lgkmcnt(0)
	v_mfma_f32_16x16x32_bf16 v[100:103], v[104:107], v[4:7], v[100:103]
	ds_read_b128 v[104:107], v134 offset:23616
	ds_read_b128 v[108:111], v134 offset:23680
	s_waitcnt lgkmcnt(1)
	v_mfma_f32_16x16x32_bf16 v[104:107], v[104:107], v[8:11], 0
	s_nop 3
	v_mul_f32_e64 v96, v102, s12
	v_mul_f32_e64 v97, v103, s12
	v_pk_mul_f32 v[102:103], v[100:101], s[12:13] op_sel_hi:[1,0]
	v_max_f32_e32 v100, v96, v97
	s_waitcnt lgkmcnt(0)
	v_mfma_f32_16x16x32_bf16 v[104:107], v[108:111], v[4:7], v[104:107]
	v_max3_f32 v113, v102, v103, v100
	s_nop 6
	v_pk_mul_f32 v[100:101], v[106:107], s[12:13] op_sel_hi:[1,0]
	v_pk_mul_f32 v[104:105], v[104:105], s[12:13] op_sel_hi:[1,0]
	v_max_f32_e32 v106, v100, v101
	v_max3_f32 v106, v104, v105, v106
	v_max3_f32 v230, v112, v113, v106
	ds_read_b128 v[106:109], v134 offset:27648
	ds_read_b128 v[110:113], v134 offset:27712
	s_waitcnt lgkmcnt(1)
	v_mfma_f32_16x16x32_bf16 v[106:109], v[106:109], v[8:11], 0
	s_waitcnt lgkmcnt(0)
	v_mfma_f32_16x16x32_bf16 v[108:111], v[110:113], v[4:7], v[106:109]
	s_nop 7
	v_pk_mul_f32 v[106:107], v[110:111], s[12:13] op_sel_hi:[1,0]
	v_pk_mul_f32 v[108:109], v[108:109], s[12:13] op_sel_hi:[1,0]
	v_max_f32_e32 v110, v106, v107
	v_max3_f32 v231, v108, v109, v110
	ds_read_b128 v[110:113], v134 offset:28224
	ds_read_b128 v[114:117], v134 offset:28288
	s_waitcnt lgkmcnt(1)
	v_mfma_f32_16x16x32_bf16 v[110:113], v[110:113], v[8:11], 0
	s_waitcnt lgkmcnt(0)
	v_mfma_f32_16x16x32_bf16 v[112:115], v[114:117], v[4:7], v[110:113]
	s_nop 7
	v_pk_mul_f32 v[110:111], v[114:115], s[12:13] op_sel_hi:[1,0]
	v_pk_mul_f32 v[112:113], v[112:113], s[12:13] op_sel_hi:[1,0]
	v_max_f32_e32 v114, v110, v111
	v_max3_f32 v114, v112, v113, v114
	v_max3_f32 v238, v230, v231, v114
	ds_read_b128 v[114:117], v134 offset:32256
	ds_read_b128 v[230:233], v134 offset:32320
	s_waitcnt lgkmcnt(1)
	v_mfma_f32_16x16x32_bf16 v[114:117], v[114:117], v[8:11], 0
	s_waitcnt lgkmcnt(0)
	v_mfma_f32_16x16x32_bf16 v[230:233], v[230:233], v[4:7], v[114:117]
	s_nop 7
	v_pk_mul_f32 v[114:115], v[232:233], s[12:13] op_sel_hi:[1,0]
	v_pk_mul_f32 v[116:117], v[230:231], s[12:13] op_sel_hi:[1,0]
	v_max_f32_e32 v230, v114, v115
	v_max3_f32 v239, v116, v117, v230
	ds_read_b128 v[230:233], v134 offset:32832
	ds_read_b128 v[234:237], v134 offset:32896
	s_waitcnt lgkmcnt(1)
	v_mfma_f32_16x16x32_bf16 v[8:11], v[230:233], v[8:11], 0
	s_waitcnt lgkmcnt(0)
	s_barrier
	v_mfma_f32_16x16x32_bf16 v[6:9], v[234:237], v[4:7], v[8:11]
	s_nop 7
	v_pk_mul_f32 v[4:5], v[8:9], s[12:13] op_sel_hi:[1,0]
	v_pk_mul_f32 v[6:7], v[6:7], s[12:13] op_sel_hi:[1,0]
	v_max_f32_e32 v8, v4, v5
	v_max3_f32 v8, v6, v7, v8
	v_max3_f32 v8, v238, v239, v8
	ds_bpermute_b32 v9, v131, v8
	s_waitcnt lgkmcnt(0)
	v_max_f32_e32 v9, v9, v9
	v_max_f32_e32 v8, v8, v9
	ds_bpermute_b32 v9, v132, v8
	s_waitcnt lgkmcnt(0)
	v_max_f32_e32 v9, v9, v9
	v_max_f32_e32 v8, v8, v9
	v_sub_f32_e32 v10, v165, v8
	v_mul_f32_e32 v10, 0x3fb8aa3b, v10
	v_exp_f32_e32 v165, v10
	v_sub_f32_e32 v10, v168, v8
	v_mul_f32_e32 v10, 0x3fb8aa3b, v10
	v_exp_f32_e32 v168, v10
	v_sub_f32_e32 v10, v167, v8
	v_mul_f32_e32 v10, 0x3fb8aa3b, v10
	v_exp_f32_e32 v167, v10
	v_sub_f32_e32 v10, v171, v8
	v_mul_f32_e32 v10, 0x3fb8aa3b, v10
	v_exp_f32_e32 v171, v10
	v_sub_f32_e32 v10, v169, v8
	v_mul_f32_e32 v10, 0x3fb8aa3b, v10
	v_exp_f32_e32 v230, v10
	v_sub_f32_e32 v10, v172, v8
	v_mul_f32_e32 v10, 0x3fb8aa3b, v10
	v_exp_f32_e32 v172, v10
	v_sub_f32_e32 v10, v170, v8
	v_mul_f32_e32 v10, 0x3fb8aa3b, v10
	v_exp_f32_e32 v231, v10
	v_sub_f32_e32 v10, v175, v8
	v_mul_f32_e32 v10, 0x3fb8aa3b, v10
	v_exp_f32_e32 v169, v10
	v_sub_f32_e32 v10, v173, v8
	v_mul_f32_e32 v10, 0x3fb8aa3b, v10
	v_exp_f32_e32 v170, v10
	v_sub_f32_e32 v10, v176, v8
	v_mul_f32_e32 v10, 0x3fb8aa3b, v10
	v_exp_f32_e32 v173, v10
	v_sub_f32_e32 v10, v174, v8
	v_mul_f32_e32 v10, 0x3fb8aa3b, v10
	v_exp_f32_e32 v174, v10
	v_sub_f32_e32 v10, v179, v8
	v_mul_f32_e32 v10, 0x3fb8aa3b, v10
	v_exp_f32_e32 v175, v10
	v_sub_f32_e32 v10, v177, v8
	v_mul_f32_e32 v10, 0x3fb8aa3b, v10
	v_exp_f32_e32 v177, v10
	v_sub_f32_e32 v10, v180, v8
	v_mul_f32_e32 v10, 0x3fb8aa3b, v10
	v_exp_f32_e32 v179, v10
	v_sub_f32_e32 v10, v178, v8
	v_mul_f32_e32 v10, 0x3fb8aa3b, v10
	v_exp_f32_e32 v232, v10
	v_sub_f32_e32 v10, v183, v8
	v_mul_f32_e32 v10, 0x3fb8aa3b, v10
	v_exp_f32_e32 v176, v10
	v_sub_f32_e32 v10, v181, v8
	v_mul_f32_e32 v10, 0x3fb8aa3b, v10
	v_exp_f32_e32 v178, v10
	v_sub_f32_e32 v10, v184, v8
	v_mul_f32_e32 v10, 0x3fb8aa3b, v10
	v_exp_f32_e32 v180, v10
	v_sub_f32_e32 v10, v182, v8
	v_mul_f32_e32 v10, 0x3fb8aa3b, v10
	v_exp_f32_e32 v181, v10
	v_sub_f32_e32 v10, v187, v8
	v_mul_f32_e32 v10, 0x3fb8aa3b, v10
	v_exp_f32_e32 v182, v10
	v_sub_f32_e32 v10, v185, v8
	v_mul_f32_e32 v10, 0x3fb8aa3b, v10
	v_exp_f32_e32 v184, v10
	v_sub_f32_e32 v10, v189, v8
	v_mul_f32_e32 v10, 0x3fb8aa3b, v10
	v_exp_f32_e32 v187, v10
	v_sub_f32_e32 v10, v186, v8
	v_mul_f32_e32 v10, 0x3fb8aa3b, v10
	v_exp_f32_e32 v189, v10
	v_sub_f32_e32 v10, v192, v8
	v_mul_f32_e32 v10, 0x3fb8aa3b, v10
	v_exp_f32_e32 v183, v10
	v_sub_f32_e32 v10, v190, v8
	v_mul_f32_e32 v10, 0x3fb8aa3b, v10
	v_exp_f32_e32 v185, v10
	v_sub_f32_e32 v10, v193, v8
	v_mul_f32_e32 v10, 0x3fb8aa3b, v10
	v_exp_f32_e32 v186, v10
	v_sub_f32_e32 v10, v191, v8
	v_mul_f32_e32 v10, 0x3fb8aa3b, v10
	v_exp_f32_e32 v190, v10
	v_sub_f32_e32 v10, v196, v8
	v_mul_f32_e32 v10, 0x3fb8aa3b, v10
	v_exp_f32_e32 v191, v10
	v_sub_f32_e32 v10, v194, v8
	v_mul_f32_e32 v10, 0x3fb8aa3b, v10
	v_exp_f32_e32 v193, v10
	v_sub_f32_e32 v10, v197, v8
	v_mul_f32_e32 v10, 0x3fb8aa3b, v10
	v_exp_f32_e32 v196, v10
	v_sub_f32_e32 v10, v195, v8
	v_mul_f32_e32 v10, 0x3fb8aa3b, v10
	v_exp_f32_e32 v197, v10
	v_sub_f32_e32 v10, v200, v8
	v_mul_f32_e32 v10, 0x3fb8aa3b, v10
	v_exp_f32_e32 v192, v10
	v_sub_f32_e32 v10, v198, v8
	v_mul_f32_e32 v10, 0x3fb8aa3b, v10
	v_exp_f32_e32 v194, v10
	v_sub_f32_e32 v10, v201, v8
	v_mul_f32_e32 v10, 0x3fb8aa3b, v10
	v_exp_f32_e32 v195, v10
	v_sub_f32_e32 v10, v199, v8
	v_mul_f32_e32 v10, 0x3fb8aa3b, v10
	v_exp_f32_e32 v198, v10
	v_sub_f32_e32 v10, v204, v8
	v_mul_f32_e32 v10, 0x3fb8aa3b, v10
	v_exp_f32_e32 v199, v10
	v_sub_f32_e32 v10, v202, v8
	v_mul_f32_e32 v10, 0x3fb8aa3b, v10
	v_exp_f32_e32 v201, v10
	v_sub_f32_e32 v10, v205, v8
	v_mul_f32_e32 v10, 0x3fb8aa3b, v10
	v_exp_f32_e32 v204, v10
	v_sub_f32_e32 v10, v203, v8
	v_mul_f32_e32 v10, 0x3fb8aa3b, v10
	v_exp_f32_e32 v205, v10
	v_sub_f32_e32 v10, v208, v8
	v_mul_f32_e32 v10, 0x3fb8aa3b, v10
	v_exp_f32_e32 v200, v10
	v_sub_f32_e32 v10, v206, v8
	v_mul_f32_e32 v10, 0x3fb8aa3b, v10
	v_exp_f32_e32 v202, v10
	v_sub_f32_e32 v10, v209, v8
	v_mul_f32_e32 v10, 0x3fb8aa3b, v10
	v_exp_f32_e32 v203, v10
	v_sub_f32_e32 v10, v207, v8
	v_mul_f32_e32 v10, 0x3fb8aa3b, v10
	v_exp_f32_e32 v206, v10
	v_sub_f32_e32 v10, v212, v8
	v_mul_f32_e32 v10, 0x3fb8aa3b, v10
	v_exp_f32_e32 v207, v10
	v_sub_f32_e32 v10, v210, v8
	v_mul_f32_e32 v10, 0x3fb8aa3b, v10
	v_exp_f32_e32 v209, v10
	v_sub_f32_e32 v10, v213, v8
	v_mul_f32_e32 v10, 0x3fb8aa3b, v10
	v_exp_f32_e32 v212, v10
	v_sub_f32_e32 v10, v211, v8
	v_mul_f32_e32 v10, 0x3fb8aa3b, v10
	v_exp_f32_e32 v233, v10
	v_sub_f32_e32 v10, v216, v8
	v_mul_f32_e32 v10, 0x3fb8aa3b, v10
	v_exp_f32_e32 v208, v10
	v_sub_f32_e32 v10, v214, v8
	v_mul_f32_e32 v10, 0x3fb8aa3b, v10
	v_exp_f32_e32 v210, v10
	v_sub_f32_e32 v10, v217, v8
	v_mul_f32_e32 v10, 0x3fb8aa3b, v10
	v_exp_f32_e32 v211, v10
	v_sub_f32_e32 v10, v215, v8
	v_mul_f32_e32 v10, 0x3fb8aa3b, v10
	v_exp_f32_e32 v214, v10
	v_sub_f32_e32 v10, v220, v8
	v_mul_f32_e32 v10, 0x3fb8aa3b, v10
	v_exp_f32_e32 v215, v10
	v_sub_f32_e32 v10, v218, v8
	v_mul_f32_e32 v10, 0x3fb8aa3b, v10
	v_exp_f32_e32 v217, v10
	v_sub_f32_e32 v10, v221, v8
	v_mul_f32_e32 v10, 0x3fb8aa3b, v10
	v_exp_f32_e32 v220, v10
	v_sub_f32_e32 v10, v219, v8
	v_mul_f32_e32 v10, 0x3fb8aa3b, v10
	v_exp_f32_e32 v234, v10
	v_sub_f32_e32 v10, v224, v8
	v_mul_f32_e32 v10, 0x3fb8aa3b, v10
	v_exp_f32_e32 v213, v10
	v_sub_f32_e32 v10, v222, v8
	v_mul_f32_e32 v10, 0x3fb8aa3b, v10
	v_exp_f32_e32 v216, v10
	v_sub_f32_e32 v10, v225, v8
	v_mul_f32_e32 v10, 0x3fb8aa3b, v10
	v_exp_f32_e32 v218, v10
	v_sub_f32_e32 v10, v223, v8
	v_mul_f32_e32 v10, 0x3fb8aa3b, v10
	v_exp_f32_e32 v221, v10
	v_sub_f32_e32 v10, v228, v8
	v_mul_f32_e32 v10, 0x3fb8aa3b, v10
	v_exp_f32_e32 v222, v10
	v_sub_f32_e32 v10, v226, v8
	v_sub_f32_e32 v9, v166, v8
	v_mul_f32_e32 v10, 0x3fb8aa3b, v10
	v_mul_f32_e32 v9, 0x3fb8aa3b, v9
	v_exp_f32_e32 v224, v10
	v_sub_f32_e32 v10, v229, v8
	v_exp_f32_e32 v166, v9
	v_mul_f32_e32 v10, 0x3fb8aa3b, v10
	v_exp_f32_e32 v226, v10
	v_sub_f32_e32 v10, v227, v8
	v_mul_f32_e32 v10, 0x3fb8aa3b, v10
	v_exp_f32_e32 v229, v10
	v_sub_f32_e32 v10, v18, v8
	v_add_f32_e32 v9, 0, v166
	v_mul_f32_e32 v10, 0x3fb8aa3b, v10
	v_add_f32_e32 v9, v165, v9
	v_exp_f32_e32 v219, v10
	v_sub_f32_e32 v10, v19, v8
	v_add_f32_e32 v9, v168, v9
	v_mul_f32_e32 v10, 0x3fb8aa3b, v10
	v_add_f32_e32 v9, v167, v9
	v_exp_f32_e32 v223, v10
	v_sub_f32_e32 v10, v12, v8
	v_add_f32_e32 v9, v171, v9
	v_mul_f32_e32 v10, 0x3fb8aa3b, v10
	v_add_f32_e32 v9, v230, v9
	v_exp_f32_e32 v225, v10
	v_sub_f32_e32 v10, v13, v8
	v_add_f32_e32 v9, v172, v9
	v_mul_f32_e32 v10, 0x3fb8aa3b, v10
	v_add_f32_e32 v9, v231, v9
	v_exp_f32_e32 v227, v10
	v_sub_f32_e32 v10, v22, v8
	v_add_f32_e32 v9, v169, v9
	v_mul_f32_e32 v10, 0x3fb8aa3b, v10
	v_add_f32_e32 v9, v170, v9
	v_exp_f32_e32 v228, v10
	v_sub_f32_e32 v10, v23, v8
	v_add_f32_e32 v9, v173, v9
	v_mul_f32_e32 v10, 0x3fb8aa3b, v10
	v_add_f32_e32 v9, v174, v9
	v_exp_f32_e32 v235, v10
	v_sub_f32_e32 v10, v14, v8
	v_add_f32_e32 v9, v175, v9
	v_mul_f32_e32 v10, 0x3fb8aa3b, v10
	v_add_f32_e32 v9, v177, v9
	v_exp_f32_e32 v236, v10
	v_sub_f32_e32 v10, v15, v8
	v_add_f32_e32 v9, v179, v9
	v_mul_f32_e32 v10, 0x3fb8aa3b, v10
	v_add_f32_e32 v9, v232, v9
	v_exp_f32_e32 v237, v10
	v_sub_f32_e32 v10, v26, v8
	v_add_f32_e32 v9, v176, v9
	v_mul_f32_e32 v10, 0x3fb8aa3b, v10
	v_add_f32_e32 v9, v178, v9
	v_exp_f32_e32 v22, v10
	v_sub_f32_e32 v10, v27, v8
	v_add_f32_e32 v9, v180, v9
	v_mul_f32_e32 v10, 0x3fb8aa3b, v10
	v_add_f32_e32 v9, v181, v9
	v_exp_f32_e32 v23, v10
	v_sub_f32_e32 v10, v20, v8
	v_add_f32_e32 v9, v182, v9
	v_mul_f32_e32 v10, 0x3fb8aa3b, v10
	v_add_f32_e32 v9, v184, v9
	v_exp_f32_e32 v20, v10
	v_sub_f32_e32 v10, v21, v8
	v_add_f32_e32 v9, v187, v9
	v_mul_f32_e32 v10, 0x3fb8aa3b, v10
	v_add_f32_e32 v9, v189, v9
	v_exp_f32_e32 v26, v10
	v_sub_f32_e32 v10, v30, v8
	v_add_f32_e32 v9, v183, v9
	v_mul_f32_e32 v10, 0x3fb8aa3b, v10
	v_add_f32_e32 v9, v185, v9
	v_exp_f32_e32 v27, v10
	v_sub_f32_e32 v10, v31, v8
	v_add_f32_e32 v9, v186, v9
	v_mul_f32_e32 v10, 0x3fb8aa3b, v10
	v_add_f32_e32 v9, v190, v9
	v_exp_f32_e32 v30, v10
	v_sub_f32_e32 v10, v24, v8
	v_add_f32_e32 v9, v191, v9
	v_mul_f32_e32 v10, 0x3fb8aa3b, v10
	v_add_f32_e32 v9, v193, v9
	v_exp_f32_e32 v31, v10
	v_sub_f32_e32 v10, v25, v8
	v_add_f32_e32 v9, v196, v9
	v_mul_f32_e32 v10, 0x3fb8aa3b, v10
	v_add_f32_e32 v9, v197, v9
	v_exp_f32_e32 v238, v10
	v_sub_f32_e32 v10, v34, v8
	v_add_f32_e32 v9, v192, v9
	v_mul_f32_e32 v10, 0x3fb8aa3b, v10
	v_add_f32_e32 v9, v194, v9
	v_exp_f32_e32 v21, v10
	v_sub_f32_e32 v10, v35, v8
	v_add_f32_e32 v9, v195, v9
	v_mul_f32_e32 v10, 0x3fb8aa3b, v10
	v_add_f32_e32 v9, v198, v9
	v_exp_f32_e32 v24, v10
	v_sub_f32_e32 v10, v28, v8
	v_add_f32_e32 v9, v199, v9
	v_mul_f32_e32 v10, 0x3fb8aa3b, v10
	v_add_f32_e32 v9, v201, v9
	v_exp_f32_e32 v25, v10
	v_sub_f32_e32 v10, v29, v8
	v_add_f32_e32 v9, v204, v9
	v_mul_f32_e32 v10, 0x3fb8aa3b, v10
	v_add_f32_e32 v9, v205, v9
	v_exp_f32_e32 v28, v10
	v_sub_f32_e32 v10, v82, v8
	v_add_f32_e32 v9, v200, v9
	v_mul_f32_e32 v10, 0x3fb8aa3b, v10
	v_add_f32_e32 v9, v202, v9
	v_exp_f32_e32 v34, v10
	v_sub_f32_e32 v10, v83, v8
	v_add_f32_e32 v9, v203, v9
	v_mul_f32_e32 v10, 0x3fb8aa3b, v10
	v_add_f32_e32 v9, v206, v9
	v_exp_f32_e32 v35, v10
	v_sub_f32_e32 v10, v32, v8
	v_add_f32_e32 v9, v207, v9
	v_mul_f32_e32 v10, 0x3fb8aa3b, v10
	v_add_f32_e32 v9, v209, v9
	v_exp_f32_e32 v82, v10
	v_sub_f32_e32 v10, v33, v8
	v_add_f32_e32 v9, v212, v9
	v_mul_f32_e32 v10, 0x3fb8aa3b, v10
	v_add_f32_e32 v9, v233, v9
	v_exp_f32_e32 v83, v10
	v_sub_f32_e32 v10, v86, v8
	v_add_f32_e32 v9, v208, v9
	v_mul_f32_e32 v10, 0x3fb8aa3b, v10
	v_add_f32_e32 v9, v210, v9
	v_exp_f32_e32 v29, v10
	v_sub_f32_e32 v10, v87, v8
	v_add_f32_e32 v9, v211, v9
	v_mul_f32_e32 v10, 0x3fb8aa3b, v10
	v_add_f32_e32 v9, v214, v9
	v_exp_f32_e32 v32, v10
	v_sub_f32_e32 v10, v80, v8
	v_add_f32_e32 v9, v215, v9
	v_mul_f32_e32 v10, 0x3fb8aa3b, v10
	v_add_f32_e32 v9, v217, v9
	v_exp_f32_e32 v33, v10
	v_sub_f32_e32 v10, v81, v8
	v_add_f32_e32 v9, v220, v9
	v_mul_f32_e32 v10, 0x3fb8aa3b, v10
	v_add_f32_e32 v9, v234, v9
	v_exp_f32_e32 v80, v10
	v_sub_f32_e32 v10, v90, v8
	v_add_f32_e32 v9, v213, v9
	v_mul_f32_e32 v10, 0x3fb8aa3b, v10
	v_add_f32_e32 v9, v216, v9
	v_exp_f32_e32 v86, v10
	v_sub_f32_e32 v10, v91, v8
	v_add_f32_e32 v9, v218, v9
	v_mul_f32_e32 v10, 0x3fb8aa3b, v10
	v_add_f32_e32 v9, v221, v9
	v_exp_f32_e32 v87, v10
	v_sub_f32_e32 v10, v84, v8
	v_add_f32_e32 v9, v222, v9
	v_mul_f32_e32 v10, 0x3fb8aa3b, v10
	v_add_f32_e32 v9, v224, v9
	v_exp_f32_e32 v91, v10
	v_sub_f32_e32 v10, v85, v8
	v_add_f32_e32 v9, v226, v9
	v_mul_f32_e32 v10, 0x3fb8aa3b, v10
	v_add_f32_e32 v9, v229, v9
	v_exp_f32_e32 v239, v10
	v_sub_f32_e32 v10, v94, v8
	v_add_f32_e32 v9, v219, v9
	v_mul_f32_e32 v10, 0x3fb8aa3b, v10
	v_add_f32_e32 v9, v223, v9
	v_exp_f32_e32 v81, v10
	v_sub_f32_e32 v10, v95, v8
	v_add_f32_e32 v9, v225, v9
	v_mul_f32_e32 v10, 0x3fb8aa3b, v10
	v_add_f32_e32 v9, v227, v9
	v_exp_f32_e32 v84, v10
	v_sub_f32_e32 v10, v88, v8
	v_add_f32_e32 v9, v228, v9
	v_mul_f32_e32 v10, 0x3fb8aa3b, v10
	v_add_f32_e32 v9, v235, v9
	v_exp_f32_e32 v90, v10
	v_sub_f32_e32 v10, v89, v8
	v_add_f32_e32 v9, v236, v9
	v_mul_f32_e32 v10, 0x3fb8aa3b, v10
	v_add_f32_e32 v9, v237, v9
	v_exp_f32_e32 v89, v10
	v_sub_f32_e32 v10, v98, v8
	v_add_f32_e32 v9, v22, v9
	v_mul_f32_e32 v10, 0x3fb8aa3b, v10
	v_add_f32_e32 v9, v23, v9
	v_exp_f32_e32 v94, v10
	v_sub_f32_e32 v10, v99, v8
	v_add_f32_e32 v9, v20, v9
	v_mul_f32_e32 v10, 0x3fb8aa3b, v10
	v_add_f32_e32 v9, v26, v9
	v_exp_f32_e32 v98, v10
	v_sub_f32_e32 v10, v92, v8
	v_add_f32_e32 v9, v27, v9
	v_mul_f32_e32 v10, 0x3fb8aa3b, v10
	v_add_f32_e32 v9, v30, v9
	v_exp_f32_e32 v240, v10
	v_sub_f32_e32 v10, v93, v8
	v_add_f32_e32 v9, v31, v9
	v_mul_f32_e32 v10, 0x3fb8aa3b, v10
	v_add_f32_e32 v9, v238, v9
	v_exp_f32_e32 v242, v10
	v_sub_f32_e32 v10, v102, v8
	v_add_f32_e32 v9, v21, v9
	v_mul_f32_e32 v10, 0x3fb8aa3b, v10
	v_add_f32_e32 v9, v24, v9
	v_exp_f32_e32 v92, v10
	v_sub_f32_e32 v10, v103, v8
	v_add_f32_e32 v9, v25, v9
	v_mul_f32_e32 v10, 0x3fb8aa3b, v10
	v_add_f32_e32 v9, v28, v9
	v_exp_f32_e32 v93, v10
	v_sub_f32_e32 v10, v96, v8
	v_add_f32_e32 v9, v34, v9
	v_mul_f32_e32 v10, 0x3fb8aa3b, v10
	v_add_f32_e32 v9, v35, v9
	v_exp_f32_e32 v102, v10
	v_sub_f32_e32 v10, v97, v8
	v_add_f32_e32 v9, v82, v9
	v_mul_f32_e32 v10, 0x3fb8aa3b, v10
	v_add_f32_e32 v9, v83, v9
	v_exp_f32_e32 v241, v10
	v_sub_f32_e32 v10, v104, v8
	v_add_f32_e32 v9, v29, v9
	v_mul_f32_e32 v10, 0x3fb8aa3b, v10
	v_add_f32_e32 v9, v32, v9
	v_exp_f32_e32 v243, v10
	v_sub_f32_e32 v10, v105, v8
	v_add_f32_e32 v9, v33, v9
	v_mul_f32_e32 v10, 0x3fb8aa3b, v10
	v_add_f32_e32 v9, v80, v9
	v_exp_f32_e32 v244, v10
	v_sub_f32_e32 v10, v100, v8
	v_add_f32_e32 v9, v86, v9
	v_mul_f32_e32 v10, 0x3fb8aa3b, v10
	v_add_f32_e32 v9, v87, v9
	v_exp_f32_e32 v245, v10
	v_sub_f32_e32 v10, v101, v8
	v_add_f32_e32 v9, v91, v9
	v_mul_f32_e32 v10, 0x3fb8aa3b, v10
	v_add_f32_e32 v9, v239, v9
	v_exp_f32_e32 v246, v10
	v_sub_f32_e32 v10, v108, v8
	v_add_f32_e32 v9, v81, v9
	v_mul_f32_e32 v10, 0x3fb8aa3b, v10
	v_add_f32_e32 v9, v84, v9
	v_exp_f32_e32 v105, v10
	v_sub_f32_e32 v10, v109, v8
	v_add_f32_e32 v9, v90, v9
	v_mul_f32_e32 v10, 0x3fb8aa3b, v10
	v_add_f32_e32 v9, v89, v9
	v_exp_f32_e32 v108, v10
	v_sub_f32_e32 v10, v106, v8
	v_add_f32_e32 v9, v94, v9
	v_mul_f32_e32 v10, 0x3fb8aa3b, v10
	v_add_f32_e32 v9, v98, v9
	v_exp_f32_e32 v106, v10
	v_sub_f32_e32 v10, v107, v8
	v_add_f32_e32 v9, v240, v9
	v_mul_f32_e32 v10, 0x3fb8aa3b, v10
	v_add_f32_e32 v9, v242, v9
	v_exp_f32_e32 v107, v10
	v_sub_f32_e32 v10, v112, v8
	v_add_f32_e32 v9, v92, v9
	v_mul_f32_e32 v10, 0x3fb8aa3b, v10
	v_add_f32_e32 v9, v93, v9
	v_exp_f32_e32 v109, v10
	v_sub_f32_e32 v10, v113, v8
	v_add_f32_e32 v9, v102, v9
	v_mul_f32_e32 v10, 0x3fb8aa3b, v10
	v_add_f32_e32 v9, v241, v9
	v_exp_f32_e32 v112, v10
	v_sub_f32_e32 v10, v110, v8
	v_add_f32_e32 v9, v243, v9
	v_mul_f32_e32 v10, 0x3fb8aa3b, v10
	v_add_f32_e32 v9, v244, v9
	v_exp_f32_e32 v110, v10
	v_sub_f32_e32 v10, v111, v8
	v_add_f32_e32 v9, v245, v9
	v_mul_f32_e32 v10, 0x3fb8aa3b, v10
	v_add_f32_e32 v9, v246, v9
	v_exp_f32_e32 v111, v10
	v_sub_f32_e32 v10, v116, v8
	v_add_f32_e32 v9, v105, v9
	v_mul_f32_e32 v10, 0x3fb8aa3b, v10
	v_add_f32_e32 v9, v108, v9
	v_exp_f32_e32 v95, v10
	v_sub_f32_e32 v10, v117, v8
	v_add_f32_e32 v9, v106, v9
	v_mul_f32_e32 v10, 0x3fb8aa3b, v10
	v_add_f32_e32 v9, v107, v9
	v_exp_f32_e32 v97, v10
	v_sub_f32_e32 v10, v114, v8
	v_add_f32_e32 v9, v109, v9
	v_mul_f32_e32 v10, 0x3fb8aa3b, v10
	v_add_f32_e32 v9, v112, v9
	v_exp_f32_e32 v96, v10
	v_sub_f32_e32 v10, v115, v8
	v_add_f32_e32 v9, v110, v9
	v_mul_f32_e32 v10, 0x3fb8aa3b, v10
	v_sub_f32_e32 v6, v6, v8
	v_add_f32_e32 v9, v111, v9
	v_exp_f32_e32 v99, v10
	v_mul_f32_e32 v6, 0x3fb8aa3b, v6
	v_sub_f32_e32 v7, v7, v8
	v_add_f32_e32 v9, v95, v9
	v_exp_f32_e32 v100, v6
	v_mul_f32_e32 v7, 0x3fb8aa3b, v7
	v_sub_f32_e32 v4, v4, v8
	v_add_f32_e32 v9, v97, v9
	v_exp_f32_e32 v101, v7
	v_mul_f32_e32 v4, 0x3fb8aa3b, v4
	v_sub_f32_e32 v5, v5, v8
	v_add_f32_e32 v9, v96, v9
	v_exp_f32_e32 v103, v4
	v_mul_f32_e32 v5, 0x3fb8aa3b, v5
	v_add_f32_e32 v9, v99, v9
	v_exp_f32_e32 v104, v5
	v_add_f32_e32 v6, v100, v9
	v_add_f32_e32 v6, v101, v6
	v_add_f32_e32 v4, v103, v6
	v_add_f32_e32 v4, v104, v4
	ds_bpermute_b32 v5, v131, v4
	s_waitcnt lgkmcnt(0)
	v_add_f32_e32 v85, v4, v5
	v_lshl_add_u64 v[4:5], v[148:149], 1, v[58:59]
	v_lshlrev_b32_e32 v148, 1, v164
	v_lshl_add_u64 v[18:19], v[58:59], 0, v[148:149]
	global_load_dwordx4 v[4:7], v[4:5], off
	s_nop 0
	global_load_dwordx4 v[8:11], v[18:19], off offset:-384
	global_load_dwordx4 v[12:15], v[18:19], off offset:-256
	global_load_dwordx4 v[114:117], v[18:19], off offset:-128
	global_load_dwordx4 v[248:251], v[18:19], off
	s_waitcnt vmcnt(4)
	ds_write_b128 v136, v[4:7]
	s_waitcnt vmcnt(3)
	ds_write_b128 v136, v[8:11] offset:128
	s_waitcnt vmcnt(2)
	ds_write_b128 v136, v[12:15] offset:256
	s_waitcnt vmcnt(1)
	ds_write_b128 v136, v[114:117] offset:384
	s_waitcnt vmcnt(0)
	ds_write_b128 v136, v[248:251] offset:512
	global_load_dwordx4 v[4:7], v[18:19], off offset:128
	global_load_dwordx4 v[8:11], v[18:19], off offset:256
	global_load_dwordx4 v[12:15], v[18:19], off offset:384
	ds_bpermute_b32 v88, v132, v85
	s_cbranch_vccnz .LBB0_387
	global_load_dwordx4 v[114:117], v[18:19], off offset:512
	s_waitcnt vmcnt(0)
	ds_write_b128 v136, v[114:117] offset:1024
	s_branch .LBB0_387
